# speedup vs baseline: 1.0204x; 1.0204x over previous
; DEV void finishSM(f32x16& p0, f32x16& p1, float alpha, float& l_reg, bf16x8& pa0, bf16x8& pa1, bf16x8& pa2, bf16x8& pa3) {
; #pragma unroll
;   for (int r = 0; r < 16; ++r) p1[r] = __builtin_amdgcn_exp2f(p1[r]);
;   float ps = 0;
; #pragma unroll
;   for (int r = 0; r < 16; ++r) ps += p0[r];
; #pragma unroll
;   for (int r = 0; r < 16; ++r) ps += p1[r];
;   { auto rr = __builtin_amdgcn_permlane32_swap(__float_as_uint(ps), __float_as_uint(ps), false, false);
;     ps = __uint_as_float(rr[0]) + __uint_as_float(rr[1]); }
;   l_reg = l_reg * alpha + ps;
;     ...
;   PK4(p0, 0, pa0); PK4(p0, 8, pa1); PK4(p1, 0, pa2); PK4(p1, 8, pa3);
; DEV void qkt(f32x16& p0, f32x16& p1, const char* Ks, const char* KPs, const bf16x8* qr, const char* qpl, int r32, int hi) {
;   p0 = f32x16{}; p1 = f32x16{};
; #pragma unroll
;   for (int d0 = 0; d0 < 8; ++d0) { int cb = (d0 * 16 + hi * 8) * 2;
;     bf16x8 b0 = *reinterpret_cast<const bf16x8*>(Ks + KSWZ(r32, cb));
;     bf16x8 b1 = *reinterpret_cast<const bf16x8*>(Ks + KSWZ(32 + r32, cb));
;     bf16x8 qq = d0 < NQR ? qr[d0 < NQR ? d0 : 0] : *reinterpret_cast<const bf16x8*>(qpl + (d0 - NQR) * 1024);
;     p0 = __builtin_amdgcn_mfma_f32_32x32x16_bf16(b0, qq, p0, 0, 0, 0);
;     p1 = __builtin_amdgcn_mfma_f32_32x32x16_bf16(b1, qq, p1, 0, 0, 0); }
; #pragma unroll
;   for (int d1 = 0; d1 < 4; ++d1) { int cb = (d1 * 16 + hi * 8) * 2;
;     bf16x8 b0 = *reinterpret_cast<const bf16x8*>(KPs + KPSWZ(r32, cb));
;     bf16x8 b1 = *reinterpret_cast<const bf16x8*>(KPs + KPSWZ(32 + r32, cb));
;     bf16x8 qp = *reinterpret_cast<const bf16x8*>(qpl + (8 - NQR + d1) * 1024);
;     p0 = __builtin_amdgcn_mfma_f32_32x32x16_bf16(b0, qp, p0, 0, 0, 0);
;     p1 = __builtin_amdgcn_mfma_f32_32x32x16_bf16(b1, qp, p1, 0, 0, 0); }
; }
.LBB0_304:
	ds_read_b128 v[64:67], v159 offset:49152
	ds_read_b128 v[68:71], v159 offset:57344
	ds_read_b128 v[188:191], v162 offset:49152
	ds_read_b128 v[202:205], v162 offset:57344
	s_waitcnt vmcnt(0)
	ds_write_b128 v154, v[238:241] offset:16384
	ds_write_b128 v155, v[242:245] offset:16384
	s_mov_b32 s0, 0x40000
	v_add_co_u32_e32 v224, vcc, s0, v142
	s_nop 1
	v_addc_co_u32_e32 v225, vcc, 0, v143, vcc
	global_load_dwordx4 v[226:229], v[142:143], off
	global_load_dwordx4 v[230:233], v[224:225], off
	global_load_dwordx4 v[234:237], v[140:141], off
	global_load_dwordx4 v[238:241], v[142:143], off offset:256
	global_load_dwordx4 v[242:245], v[224:225], off offset:256
	v_add_f32_e32 v133, 0, v196
	v_add_f32_e32 v133, v199, v133
	s_waitcnt lgkmcnt(5)
	v_mfma_f32_32x32x16_bf16 v[80:95], v[64:67], v[108:111], 0
	v_add_f32_e32 v133, v197, v133
	v_add_f32_e32 v133, v200, v133
	v_add_f32_e32 v133, v198, v133
	v_add_f32_e32 v133, v201, v133
	v_add_f32_e32 v133, v194, v133
	v_add_f32_e32 v133, v195, v133
	v_add_f32_e32 v133, v134, v133
	s_waitcnt lgkmcnt(4)
	v_mfma_f32_32x32x16_bf16 v[64:79], v[68:71], v[108:111], 0
	v_add_f32_e32 v133, v192, v133
	v_add_f32_e32 v133, v135, v133
	v_add_f32_e32 v133, v193, v133
	v_exp_f32_e32 v126, v126
	v_add_f32_e32 v133, v128, v133
	v_exp_f32_e32 v127, v127
	v_add_f32_e32 v133, v130, v133
	s_waitcnt lgkmcnt(0)
	v_mfma_f32_32x32x16_bf16 v[64:79], v[202:205], v[104:107], v[64:79]
	v_exp_f32_e32 v124, v124
	v_add_f32_e32 v133, v129, v133
	v_exp_f32_e32 v125, v125
	v_add_f32_e32 v133, v131, v133
	v_or_b32_e32 v187, 0x12000, v175
	v_exp_f32_e32 v120, v120
	v_add_f32_e32 v133, v126, v133
	v_mfma_f32_32x32x16_bf16 v[80:95], v[188:191], v[104:107], v[80:95]
	ds_read_b128 v[188:191], v163 offset:49152
	ds_read_b128 v[202:205], v163 offset:57344
	v_exp_f32_e32 v121, v121
	v_add_f32_e32 v133, v127, v133
	v_exp_f32_e32 v116, v116
	v_add_f32_e32 v133, v124, v133
	v_exp_f32_e32 v117, v117
	v_add_f32_e32 v133, v125, v133
	s_waitcnt lgkmcnt(0)
	v_mfma_f32_32x32x16_bf16 v[64:79], v[202:205], v[100:103], v[64:79]
	v_exp_f32_e32 v112, v112
	v_add_f32_e32 v133, v120, v133
	v_exp_f32_e32 v113, v113
	v_add_f32_e32 v133, v121, v133
	v_exp_f32_e32 v122, v122
	v_add_f32_e32 v133, v116, v133
	v_exp_f32_e32 v123, v123
	v_mfma_f32_32x32x16_bf16 v[80:95], v[188:191], v[100:103], v[80:95]
	ds_read_b128 v[188:191], v166 offset:49152
	ds_read_b128 v[202:205], v166 offset:57344
	v_add_f32_e32 v133, v117, v133
	v_exp_f32_e32 v118, v118
	v_add_f32_e32 v133, v112, v133
	v_exp_f32_e32 v119, v119
	v_add_f32_e32 v133, v113, v133
	v_exp_f32_e32 v114, v114
	s_waitcnt lgkmcnt(0)
	v_mfma_f32_32x32x16_bf16 v[64:79], v[202:205], v[96:99], v[64:79]
	v_add_f32_e32 v133, v122, v133
	v_exp_f32_e32 v115, v115
	v_add_f32_e32 v133, v123, v133
	v_add_f32_e32 v133, v118, v133
	v_add_f32_e32 v133, v119, v133
	v_add_f32_e32 v133, v114, v133
	v_mfma_f32_32x32x16_bf16 v[80:95], v[188:191], v[96:99], v[80:95]
	ds_read_b128 v[188:191], v167 offset:49152
	ds_read_b128 v[202:205], v167 offset:57344
	ds_read_b128 v[206:209], v177
	s_waitcnt lgkmcnt(0)
	v_mfma_f32_32x32x16_bf16 v[64:79], v[202:205], v[206:209], v[64:79]
	v_mfma_f32_32x32x16_bf16 v[80:95], v[188:191], v[206:209], v[80:95]
	ds_read_b128 v[188:191], v168 offset:49152
	ds_read_b128 v[202:205], v168 offset:57344
	ds_read_b128 v[206:209], v177 offset:1024
	s_waitcnt lgkmcnt(0)
	v_mfma_f32_32x32x16_bf16 v[64:79], v[202:205], v[206:209], v[64:79]
	v_mfma_f32_32x32x16_bf16 v[80:95], v[188:191], v[206:209], v[80:95]
	ds_read_b128 v[188:191], v160 offset:49152
	ds_read_b128 v[202:205], v160 offset:57344
	ds_read_b128 v[206:209], v177 offset:2048
	s_waitcnt lgkmcnt(0)
	v_mfma_f32_32x32x16_bf16 v[64:79], v[202:205], v[206:209], v[64:79]
	v_mfma_f32_32x32x16_bf16 v[80:95], v[188:191], v[206:209], v[80:95]
	ds_read_b128 v[188:191], v161 offset:49152
	ds_read_b128 v[202:205], v161 offset:57344
	ds_read_b128 v[206:209], v177 offset:3072
	s_waitcnt lgkmcnt(0)
	v_mfma_f32_32x32x16_bf16 v[64:79], v[202:205], v[206:209], v[64:79]
	v_mfma_f32_32x32x16_bf16 v[80:95], v[188:191], v[206:209], v[80:95]
	ds_read_b128 v[188:191], v184
	ds_read_b128 v[202:205], v185
	ds_read_b128 v[206:209], v177 offset:4096
	s_waitcnt lgkmcnt(0)
	v_mfma_f32_32x32x16_bf16 v[64:79], v[202:205], v[206:209], v[64:79]
	v_mfma_f32_32x32x16_bf16 v[80:95], v[188:191], v[206:209], v[80:95]
	ds_read_b128 v[188:191], v181
	ds_read_b128 v[202:205], v182
	ds_read_b128 v[206:209], v177 offset:5120
	s_waitcnt lgkmcnt(0)
	v_mfma_f32_32x32x16_bf16 v[64:79], v[202:205], v[206:209], v[64:79]
	v_mfma_f32_32x32x16_bf16 v[80:95], v[188:191], v[206:209], v[80:95]
	ds_read_b128 v[188:191], v179
	ds_read_b128 v[202:205], v180
	ds_read_b128 v[206:209], v177 offset:6144
	s_waitcnt lgkmcnt(0)
	v_mfma_f32_32x32x16_bf16 v[64:79], v[202:205], v[206:209], v[64:79]
	ds_read_b128 v[202:205], v187
	v_mfma_f32_32x32x16_bf16 v[80:95], v[188:191], v[206:209], v[80:95]
	v_or_b32_e32 v188, 0x13000, v175
	ds_read_b128 v[206:209], v188
	ds_read_b128 v[210:213], v177 offset:7168
	v_add_f32_e32 v189, v115, v133
	v_mov_b32_e32 v190, v189
	s_nop 1
	v_permlane32_swap_b32_e32 v189, v190
	v_cvt_pk_bf16_f32 v196, v196, v199
	s_waitcnt lgkmcnt(0)
; #define SBAR() __builtin_amdgcn_sched_barrier(0)
; DEV void partialSM(f32x16& p0, f32x16& p1, float& m_reg, float& mn, float& alpha) {
;   constexpr float C = SCALE * 1.4426950408889634f;
;   float pmax = p0[0];
; #pragma unroll
;   for (int r = 1; r < 16; ++r) pmax = fmaxf(pmax, p0[r]);
; #pragma unroll
;   for (int r = 0; r < 16; ++r) pmax = fmaxf(pmax, p1[r]);
;   { auto rr = __builtin_amdgcn_permlane32_swap(__float_as_uint(pmax), __float_as_uint(pmax), false, false);
;     pmax = fmaxf(__uint_as_float(rr[0]), __uint_as_float(rr[1])); }
;   if (__builtin_expect(__all(pmax - m_reg <= THR / SCALE), 1)) { mn = m_reg; alpha = 1.f; }
;   else { mn = fmaxf(m_reg, pmax); alpha = __builtin_amdgcn_exp2f((m_reg - mn) * C); m_reg = mn; }
;   float mnC = -mn * C;
; #pragma unroll
;   for (int r = 0; r < 16; ++r) p0[r] = fmaf(p0[r], C, mnC);
; #pragma unroll
;   for (int r = 0; r < 16; ++r) p1[r] = fmaf(p1[r], C, mnC);
; #pragma unroll
;   for (int r = 0; r < 16; ++r) p0[r] = __builtin_amdgcn_exp2f(p0[r]);
; }
; template <int OFF> DEV s16x4 tr_read(int vb) {
;   s16x4 r; asm volatile("ds_read_b64_tr_b16 %0, %1 offset:%2" : "=&v"(r) : "v"(vb), "i"(OFF) : "memory"); return r;
; }
; template <int D0> DEV void pv_one(f32x16& od, int vb, bf16x8 pa0, bf16x8 pa1, bf16x8 pa2, bf16x8 pa3) {
;   const s16x4 l0 = tr_read<v_rd_off(D0, 0, 0)>(vb), h0 = tr_read<v_rd_off(D0, 0, 1)>(vb), l1 = tr_read<v_rd_off(D0, 1, 0)>(vb), h1 = tr_read<v_rd_off(D0, 1, 1)>(vb);
;   const s16x4 l2 = tr_read<v_rd_off(D0, 2, 0)>(vb), h2 = tr_read<v_rd_off(D0, 2, 1)>(vb), l3 = tr_read<v_rd_off(D0, 3, 0)>(vb), h3 = tr_read<v_rd_off(D0, 3, 1)>(vb);
;   asm volatile("s_waitcnt lgkmcnt(0)" ::: "memory"); SBAR();
;     ...
;   od = __builtin_amdgcn_mfma_f32_32x32x16_bf16(pa0, PK(l0, h0), od, 0, 0, 0);
;   od = __builtin_amdgcn_mfma_f32_32x32x16_bf16(pa1, PK(l1, h1), od, 0, 0, 0);
;   od = __builtin_amdgcn_mfma_f32_32x32x16_bf16(pa2, PK(l2, h2), od, 0, 0, 0);
;   od = __builtin_amdgcn_mfma_f32_32x32x16_bf16(pa3, PK(l3, h3), od, 0, 0, 0);
;     ...
; }
; DEV void pv_d0(f32x16* o, int vb, bf16x8 pa0, bf16x8 pa1, bf16x8 pa2, bf16x8 pa3) {
;   pv_one<0>(o[0], vb, pa0, pa1, pa2, pa3); pv_one<1>(o[1], vb, pa0, pa1, pa2, pa3); pv_one<2>(o[2], vb, pa0, pa1, pa2, pa3); pv_one<3>(o[3], vb, pa0, pa1, pa2, pa3);
	v_mfma_f32_32x32x16_bf16 v[80:95], v[202:205], v[210:213], v[80:95]
	v_cvt_pk_bf16_f32 v197, v197, v200
	v_cvt_pk_bf16_f32 v198, v198, v201
	v_cvt_pk_bf16_f32 v199, v194, v195
	v_cvt_pk_bf16_f32 v192, v134, v192
	v_cvt_pk_bf16_f32 v193, v135, v193
	v_cvt_pk_bf16_f32 v194, v128, v130
	v_cvt_pk_bf16_f32 v195, v129, v131
	v_mfma_f32_32x32x16_bf16 v[64:79], v[206:209], v[210:213], v[64:79]
	v_cvt_pk_bf16_f32 v200, v126, v127
	v_cvt_pk_bf16_f32 v201, v124, v125
	v_cvt_pk_bf16_f32 v202, v120, v121
	v_cvt_pk_bf16_f32 v203, v116, v117
	v_cvt_pk_bf16_f32 v204, v112, v113
	v_cvt_pk_bf16_f32 v205, v122, v123
	v_cvt_pk_bf16_f32 v206, v118, v119
	v_cvt_pk_bf16_f32 v207, v114, v115
	v_permlane32_swap_b32_e32 v196, v198
	v_permlane32_swap_b32_e32 v197, v199
	v_permlane32_swap_b32_e32 v192, v194
	v_permlane32_swap_b32_e32 v193, v195
	v_permlane32_swap_b32_e32 v200, v202
	v_permlane32_swap_b32_e32 v201, v203
	v_permlane32_swap_b32_e32 v204, v206
	v_permlane32_swap_b32_e32 v205, v207
	s_waitcnt vmcnt(2)
	ds_write_b128 v156, v[226:229] offset:32768
	ds_write_b128 v157, v[230:233] offset:32768
	ds_write_b128 v158, v[234:237]
	ds_read_b64_tr_b16 v[208:209], v153 offset:0
	ds_read_b64_tr_b16 v[210:211], v153 offset:0x800
	ds_read_b64_tr_b16 v[212:213], v153 offset:0x1000
	ds_read_b64_tr_b16 v[214:215], v153 offset:0x1800
	ds_read_b64_tr_b16 v[216:217], v153 offset:0x2000
	ds_read_b64_tr_b16 v[218:219], v153 offset:0x2800
	ds_read_b64_tr_b16 v[220:221], v153 offset:0x3000
	ds_read_b64_tr_b16 v[222:223], v153 offset:0x3800
	s_waitcnt lgkmcnt(6)
	s_nop 0
	v_mfma_f32_32x32x16_bf16 v[0:15], v[196:199], v[208:211], v[0:15]
	ds_read_b64_tr_b16 v[208:209], v153 offset:0x200
	ds_read_b64_tr_b16 v[210:211], v153 offset:0xa00
	v_max_f32_e32 v133, v81, v81
	v_max_f32_e32 v134, v80, v80
	v_max_f32_e32 v133, v134, v133
	v_max3_f32 v133, v133, v82, v83
	v_max3_f32 v133, v133, v84, v85
	s_waitcnt lgkmcnt(6)
	v_mfma_f32_32x32x16_bf16 v[0:15], v[192:195], v[212:215], v[0:15]
	ds_read_b64_tr_b16 v[212:213], v153 offset:0x1200
	ds_read_b64_tr_b16 v[214:215], v153 offset:0x1a00
	v_max3_f32 v133, v133, v86, v87
	v_max3_f32 v133, v133, v88, v89
	v_max3_f32 v133, v133, v90, v91
	v_max3_f32 v133, v133, v92, v93
	v_max3_f32 v133, v133, v94, v95
	s_waitcnt lgkmcnt(6)
	v_mfma_f32_32x32x16_bf16 v[0:15], v[200:203], v[216:219], v[0:15]
	ds_read_b64_tr_b16 v[216:217], v153 offset:0x2200
	ds_read_b64_tr_b16 v[218:219], v153 offset:0x2a00
	v_max3_f32 v133, v133, v64, v65
	v_max3_f32 v133, v133, v66, v67
	v_max3_f32 v133, v133, v68, v69
	v_max3_f32 v133, v133, v70, v71
	v_max3_f32 v133, v133, v72, v73
	s_waitcnt lgkmcnt(6)
	v_mfma_f32_32x32x16_bf16 v[0:15], v[204:207], v[220:223], v[0:15]
	ds_read_b64_tr_b16 v[220:221], v153 offset:0x3200
	ds_read_b64_tr_b16 v[222:223], v153 offset:0x3a00
	v_max3_f32 v133, v133, v74, v75
	v_max3_f32 v133, v133, v76, v77
	v_max3_f32 v133, v133, v78, v79
	v_mov_b32_e32 v134, v133
	s_waitcnt lgkmcnt(6)
	v_mfma_f32_32x32x16_bf16 v[48:63], v[196:199], v[208:211], v[48:63]
	ds_read_b64_tr_b16 v[208:209], v153 offset:0x400
	ds_read_b64_tr_b16 v[210:211], v153 offset:0xc00
	s_nop 1
	v_permlane32_swap_b32_e32 v133, v134
	v_max_f32_e32 v134, v134, v134
	v_max_f32_e32 v133, v133, v133
	s_waitcnt lgkmcnt(6)
	v_mfma_f32_32x32x16_bf16 v[48:63], v[192:195], v[212:215], v[48:63]
	ds_read_b64_tr_b16 v[212:213], v153 offset:0x1400
	ds_read_b64_tr_b16 v[214:215], v153 offset:0x1c00
	v_max_f32_e32 v133, v133, v134
	v_sub_f32_e32 v134, v133, v132
	v_cmp_ge_f32_e32 vcc, s72, v134
	v_max_f32_e32 v134, v132, v132
	s_waitcnt lgkmcnt(6)
	v_mfma_f32_32x32x16_bf16 v[48:63], v[200:203], v[216:219], v[48:63]
	ds_read_b64_tr_b16 v[216:217], v153 offset:0x2400
	ds_read_b64_tr_b16 v[218:219], v153 offset:0x2c00
	v_max_f32_e32 v133, v134, v133
	v_sub_f32_e32 v134, v132, v133
	v_mul_f32_e32 v134, 0x3dd53b94, v134
	v_exp_f32_e32 v134, v134
	s_waitcnt lgkmcnt(6)
	v_mfma_f32_32x32x16_bf16 v[48:63], v[204:207], v[220:223], v[48:63]
	ds_read_b64_tr_b16 v[220:221], v153 offset:0x3400
	ds_read_b64_tr_b16 v[222:223], v153 offset:0x3c00
	s_cmp_eq_u64 vcc, exec
	s_cselect_b64 s[4:5], -1, 0
	v_cndmask_b32_e64 v226, v133, v132, s[4:5]
	v_mul_f32_e32 v227, 0xbdd53b94, v226
	s_waitcnt lgkmcnt(6)
	v_mfma_f32_32x32x16_bf16 v[32:47], v[196:199], v[208:211], v[32:47]
	ds_read_b64_tr_b16 v[208:209], v153 offset:0x600
	ds_read_b64_tr_b16 v[210:211], v153 offset:0xe00
	v_fmamk_f32 v80, v80, 0x3dd53b94, v227
	v_fmamk_f32 v81, v81, 0x3dd53b94, v227
	v_fmamk_f32 v82, v82, 0x3dd53b94, v227
	v_fmamk_f32 v83, v83, 0x3dd53b94, v227
	s_waitcnt lgkmcnt(6)
	v_mfma_f32_32x32x16_bf16 v[32:47], v[192:195], v[212:215], v[32:47]
	ds_read_b64_tr_b16 v[212:213], v153 offset:0x1600
	ds_read_b64_tr_b16 v[214:215], v153 offset:0x1e00
	v_fmamk_f32 v84, v84, 0x3dd53b94, v227
	v_fmamk_f32 v85, v85, 0x3dd53b94, v227
	v_fmamk_f32 v86, v86, 0x3dd53b94, v227
	v_fmamk_f32 v87, v87, 0x3dd53b94, v227
	s_waitcnt lgkmcnt(6)
	v_mfma_f32_32x32x16_bf16 v[32:47], v[200:203], v[216:219], v[32:47]
	ds_read_b64_tr_b16 v[216:217], v153 offset:0x2600
	ds_read_b64_tr_b16 v[218:219], v153 offset:0x2e00
	v_fmamk_f32 v88, v88, 0x3dd53b94, v227
	v_fmamk_f32 v89, v89, 0x3dd53b94, v227
	v_fmamk_f32 v90, v90, 0x3dd53b94, v227
	v_fmamk_f32 v91, v91, 0x3dd53b94, v227
	s_waitcnt lgkmcnt(6)
	v_mfma_f32_32x32x16_bf16 v[32:47], v[204:207], v[220:223], v[32:47]
	ds_read_b64_tr_b16 v[220:221], v153 offset:0x3600
	ds_read_b64_tr_b16 v[222:223], v153 offset:0x3e00
	v_fmamk_f32 v92, v92, 0x3dd53b94, v227
	v_fmamk_f32 v93, v93, 0x3dd53b94, v227
	v_fmamk_f32 v94, v94, 0x3dd53b94, v227
	v_fmamk_f32 v95, v95, 0x3dd53b94, v227
	s_waitcnt lgkmcnt(6)
	v_mfma_f32_32x32x16_bf16 v[16:31], v[196:199], v[208:211], v[16:31]
	v_exp_f32_e32 v125, v80
	v_exp_f32_e32 v127, v81
	v_exp_f32_e32 v123, v82
	v_exp_f32_e32 v126, v83
	s_waitcnt lgkmcnt(4)
	v_mfma_f32_32x32x16_bf16 v[16:31], v[192:195], v[212:215], v[16:31]
	v_exp_f32_e32 v122, v84
	v_exp_f32_e32 v124, v85
	v_exp_f32_e32 v120, v86
	v_exp_f32_e32 v121, v87
	s_waitcnt lgkmcnt(2)
	v_mfma_f32_32x32x16_bf16 v[16:31], v[200:203], v[216:219], v[16:31]
	v_exp_f32_e32 v117, v88
	v_exp_f32_e32 v119, v89
	v_exp_f32_e32 v116, v90
	v_exp_f32_e32 v118, v91
	s_waitcnt lgkmcnt(0)
	v_mfma_f32_32x32x16_bf16 v[16:31], v[204:207], v[220:223], v[16:31]
	v_exp_f32_e32 v113, v92
	v_exp_f32_e32 v115, v93
	v_exp_f32_e32 v112, v94
	v_exp_f32_e32 v114, v95
	v_cndmask_b32_e64 v191, v134, 1.0, s[4:5]
	v_cmp_gt_f32_e32 vcc, 1.0, v191
	s_cbranch_vccz .LBB0_308
; DEV void qkt(f32x16& p0, f32x16& p1, const char* Ks, const char* KPs, const bf16x8* qr, const char* qpl, int r32, int hi) {
;   p0 = f32x16{}; p1 = f32x16{};
; #pragma unroll
;   for (int d0 = 0; d0 < 8; ++d0) { int cb = (d0 * 16 + hi * 8) * 2;
;     bf16x8 b0 = *reinterpret_cast<const bf16x8*>(Ks + KSWZ(r32, cb));
;     bf16x8 b1 = *reinterpret_cast<const bf16x8*>(Ks + KSWZ(32 + r32, cb));
;     bf16x8 qq = d0 < NQR ? qr[d0 < NQR ? d0 : 0] : *reinterpret_cast<const bf16x8*>(qpl + (d0 - NQR) * 1024);
;     p0 = __builtin_amdgcn_mfma_f32_32x32x16_bf16(b0, qq, p0, 0, 0, 0);
;     p1 = __builtin_amdgcn_mfma_f32_32x32x16_bf16(b1, qq, p1, 0, 0, 0); }
; #pragma unroll
;   for (int d1 = 0; d1 < 4; ++d1) { int cb = (d1 * 16 + hi * 8) * 2;
;     bf16x8 b0 = *reinterpret_cast<const bf16x8*>(KPs + KPSWZ(r32, cb));
;     bf16x8 b1 = *reinterpret_cast<const bf16x8*>(KPs + KPSWZ(32 + r32, cb));
;     bf16x8 qp = *reinterpret_cast<const bf16x8*>(qpl + (8 - NQR + d1) * 1024);
;     p0 = __builtin_amdgcn_mfma_f32_32x32x16_bf16(b0, qp, p0, 0, 0, 0);
;     p1 = __builtin_amdgcn_mfma_f32_32x32x16_bf16(b1, qp, p1, 0, 0, 0); }
; }
	s_and_saveexec_b64 s[8:9], s[6:7]
	ds_write_b32 v150, v191 offset:128
	s_or_b64 exec, exec, s[8:9]
	s_waitcnt lgkmcnt(0)
	v_add_u32_e32 v228, v139, v136
	ds_read_b128 v[208:211], v228 offset:224
	ds_read_b128 v[212:215], v228 offset:192
	ds_read_b128 v[216:219], v228 offset:160
	ds_read_b128 v[220:223], v228 offset:128
	s_waitcnt lgkmcnt(3)
	v_pk_mul_f32 v[12:13], v[12:13], v[208:209]
	s_waitcnt lgkmcnt(2)
	v_pk_mul_f32 v[8:9], v[8:9], v[212:213]
	s_waitcnt lgkmcnt(1)
	v_pk_mul_f32 v[4:5], v[4:5], v[216:217]
	v_pk_mul_f32 v[14:15], v[14:15], v[210:211]
	v_pk_mul_f32 v[10:11], v[10:11], v[214:215]
	v_pk_mul_f32 v[6:7], v[6:7], v[218:219]
	s_waitcnt lgkmcnt(0)
	v_pk_mul_f32 v[2:3], v[2:3], v[222:223]
	v_pk_mul_f32 v[0:1], v[0:1], v[220:221]
	v_pk_mul_f32 v[60:61], v[60:61], v[208:209]
	v_pk_mul_f32 v[56:57], v[56:57], v[212:213]
	v_pk_mul_f32 v[52:53], v[52:53], v[216:217]
	v_pk_mul_f32 v[62:63], v[62:63], v[210:211]
	v_pk_mul_f32 v[58:59], v[58:59], v[214:215]
	v_pk_mul_f32 v[54:55], v[54:55], v[218:219]
	v_pk_mul_f32 v[50:51], v[50:51], v[222:223]
	v_pk_mul_f32 v[48:49], v[48:49], v[220:221]
	v_pk_mul_f32 v[44:45], v[44:45], v[208:209]
	v_pk_mul_f32 v[40:41], v[40:41], v[212:213]
	v_pk_mul_f32 v[36:37], v[36:37], v[216:217]
	v_pk_mul_f32 v[46:47], v[46:47], v[210:211]
	v_pk_mul_f32 v[42:43], v[42:43], v[214:215]
	v_pk_mul_f32 v[38:39], v[38:39], v[218:219]
	v_pk_mul_f32 v[34:35], v[34:35], v[222:223]
	v_pk_mul_f32 v[32:33], v[32:33], v[220:221]
	v_pk_mul_f32 v[28:29], v[28:29], v[208:209]
	v_pk_mul_f32 v[24:25], v[24:25], v[212:213]
	v_pk_mul_f32 v[20:21], v[20:21], v[216:217]
	v_pk_mul_f32 v[30:31], v[30:31], v[210:211]
	v_pk_mul_f32 v[26:27], v[26:27], v[214:215]
	v_pk_mul_f32 v[22:23], v[22:23], v[218:219]
	v_pk_mul_f32 v[18:19], v[18:19], v[222:223]
	v_pk_mul_f32 v[16:17], v[16:17], v[220:221]
.LBB0_308:
	v_cndmask_b32_e64 v192, v133, v132, s[4:5]
	v_mul_f32_e32 v128, 0xbdd53b94, v192
	v_fmamk_f32 v132, v71, 0x3dd53b94, v128
	v_fmamk_f32 v133, v72, 0x3dd53b94, v128
	v_fmamk_f32 v194, v64, 0x3dd53b94, v128
	v_fmamk_f32 v195, v65, 0x3dd53b94, v128
	v_fmamk_f32 v196, v66, 0x3dd53b94, v128
	v_fmamk_f32 v197, v67, 0x3dd53b94, v128
	v_fmamk_f32 v198, v68, 0x3dd53b94, v128
	v_fmamk_f32 v130, v69, 0x3dd53b94, v128
	v_fmamk_f32 v131, v70, 0x3dd53b94, v128
	v_fmamk_f32 v134, v73, 0x3dd53b94, v128
	v_fmamk_f32 v135, v74, 0x3dd53b94, v128
	v_fmamk_f32 v193, v75, 0x3dd53b94, v128
	v_fmamk_f32 v129, v76, 0x3dd53b94, v128
	v_fmamk_f32 v199, v77, 0x3dd53b94, v128
	v_fmamk_f32 v200, v78, 0x3dd53b94, v128
	v_fmac_f32_e32 v128, 0x3dd53b94, v79
	s_waitcnt lgkmcnt(0)
	s_barrier
	ds_read_b128 v[64:67], v159 offset:32768
	ds_read_b128 v[68:71], v159 offset:40960
	ds_read_b128 v[202:205], v162 offset:32768
	ds_read_b128 v[206:209], v162 offset:40960
	s_waitcnt vmcnt(0)
	ds_write_b128 v154, v[238:241]
	ds_write_b128 v155, v[242:245]
	v_add_co_u32_e32 v224, vcc, s73, v142
	s_mov_b32 s0, 0x22000
	s_nop 0
	v_addc_co_u32_e32 v225, vcc, 0, v143, vcc
	v_add_co_u32_e32 v222, vcc, s74, v142
	s_nop 1
	v_addc_co_u32_e32 v223, vcc, 0, v143, vcc
	v_add_co_u32_e32 v220, vcc, s0, v140
	s_nop 1
	v_addc_co_u32_e32 v221, vcc, 0, v141, vcc
	global_load_dwordx4 v[226:229], v[224:225], off
	global_load_dwordx4 v[230:233], v[222:223], off
	global_load_dwordx4 v[234:237], v[220:221], off
	global_load_dwordx4 v[238:241], v[224:225], off offset:256
	global_load_dwordx4 v[242:245], v[222:223], off offset:256
	v_exp_f32_e32 v201, v194
	v_exp_f32_e32 v130, v130
	s_waitcnt lgkmcnt(5)
	v_mfma_f32_32x32x16_bf16 v[80:95], v[64:67], v[108:111], 0
	v_exp_f32_e32 v131, v131
	v_exp_f32_e32 v193, v193
	v_exp_f32_e32 v129, v129
	v_exp_f32_e32 v128, v128
	s_waitcnt lgkmcnt(4)
	v_mfma_f32_32x32x16_bf16 v[64:79], v[68:71], v[108:111], 0
	s_waitcnt lgkmcnt(0)
	v_mfma_f32_32x32x16_bf16 v[64:79], v[206:209], v[104:107], v[64:79]
	v_mfma_f32_32x32x16_bf16 v[80:95], v[202:205], v[104:107], v[80:95]
	ds_read_b128 v[202:205], v163 offset:32768
	ds_read_b128 v[206:209], v163 offset:40960
	s_waitcnt lgkmcnt(0)
	v_mfma_f32_32x32x16_bf16 v[64:79], v[206:209], v[100:103], v[64:79]
	v_mfma_f32_32x32x16_bf16 v[80:95], v[202:205], v[100:103], v[80:95]
	ds_read_b128 v[202:205], v166 offset:32768
	ds_read_b128 v[206:209], v166 offset:40960
	s_waitcnt lgkmcnt(0)
	v_mfma_f32_32x32x16_bf16 v[64:79], v[206:209], v[96:99], v[64:79]
	v_mfma_f32_32x32x16_bf16 v[80:95], v[202:205], v[96:99], v[80:95]
	ds_read_b128 v[202:205], v167 offset:32768
	ds_read_b128 v[206:209], v167 offset:40960
	ds_read_b128 v[210:213], v177
	s_waitcnt lgkmcnt(0)
	v_mfma_f32_32x32x16_bf16 v[64:79], v[206:209], v[210:213], v[64:79]
	v_mfma_f32_32x32x16_bf16 v[80:95], v[202:205], v[210:213], v[80:95]
	ds_read_b128 v[202:205], v168 offset:32768
	ds_read_b128 v[206:209], v168 offset:40960
	ds_read_b128 v[210:213], v177 offset:1024
	s_waitcnt lgkmcnt(0)
	v_mfma_f32_32x32x16_bf16 v[64:79], v[206:209], v[210:213], v[64:79]
	v_mfma_f32_32x32x16_bf16 v[80:95], v[202:205], v[210:213], v[80:95]
	ds_read_b128 v[202:205], v160 offset:32768
	ds_read_b128 v[206:209], v160 offset:40960
	ds_read_b128 v[210:213], v177 offset:2048
	s_waitcnt lgkmcnt(0)
	v_mfma_f32_32x32x16_bf16 v[64:79], v[206:209], v[210:213], v[64:79]
	v_mfma_f32_32x32x16_bf16 v[80:95], v[202:205], v[210:213], v[80:95]
	ds_read_b128 v[202:205], v161 offset:32768
	ds_read_b128 v[206:209], v161 offset:40960
	ds_read_b128 v[210:213], v177 offset:3072
	s_waitcnt lgkmcnt(0)
	v_mfma_f32_32x32x16_bf16 v[64:79], v[206:209], v[210:213], v[64:79]
	v_mfma_f32_32x32x16_bf16 v[80:95], v[202:205], v[210:213], v[80:95]
	ds_read_b128 v[202:205], v169
	ds_read_b128 v[206:209], v170
	ds_read_b128 v[210:213], v177 offset:4096
	s_waitcnt lgkmcnt(0)
; #define SBAR() __builtin_amdgcn_sched_barrier(0)
; DEV void finishSM(f32x16& p0, f32x16& p1, float alpha, float& l_reg, bf16x8& pa0, bf16x8& pa1, bf16x8& pa2, bf16x8& pa3) {
; #pragma unroll
;   for (int r = 0; r < 16; ++r) p1[r] = __builtin_amdgcn_exp2f(p1[r]);
;   float ps = 0;
; #pragma unroll
;   for (int r = 0; r < 16; ++r) ps += p0[r];
; #pragma unroll
;   for (int r = 0; r < 16; ++r) ps += p1[r];
;   { auto rr = __builtin_amdgcn_permlane32_swap(__float_as_uint(ps), __float_as_uint(ps), false, false);
;     ps = __uint_as_float(rr[0]) + __uint_as_float(rr[1]); }
;   l_reg = l_reg * alpha + ps;
;     ...
;   PK4(p0, 0, pa0); PK4(p0, 8, pa1); PK4(p1, 0, pa2); PK4(p1, 8, pa3);
; template <int OFF> DEV s16x4 tr_read(int vb) {
;   s16x4 r; asm volatile("ds_read_b64_tr_b16 %0, %1 offset:%2" : "=&v"(r) : "v"(vb), "i"(OFF) : "memory"); return r;
; }
; template <int D0> DEV void pv_one(f32x16& od, int vb, bf16x8 pa0, bf16x8 pa1, bf16x8 pa2, bf16x8 pa3) {
;   const s16x4 l0 = tr_read<v_rd_off(D0, 0, 0)>(vb), h0 = tr_read<v_rd_off(D0, 0, 1)>(vb), l1 = tr_read<v_rd_off(D0, 1, 0)>(vb), h1 = tr_read<v_rd_off(D0, 1, 1)>(vb);
;   const s16x4 l2 = tr_read<v_rd_off(D0, 2, 0)>(vb), h2 = tr_read<v_rd_off(D0, 2, 1)>(vb), l3 = tr_read<v_rd_off(D0, 3, 0)>(vb), h3 = tr_read<v_rd_off(D0, 3, 1)>(vb);
;   asm volatile("s_waitcnt lgkmcnt(0)" ::: "memory"); SBAR();
;     ...
;   od = __builtin_amdgcn_mfma_f32_32x32x16_bf16(pa0, PK(l0, h0), od, 0, 0, 0);
;   od = __builtin_amdgcn_mfma_f32_32x32x16_bf16(pa1, PK(l1, h1), od, 0, 0, 0);
;   od = __builtin_amdgcn_mfma_f32_32x32x16_bf16(pa2, PK(l2, h2), od, 0, 0, 0);
;   od = __builtin_amdgcn_mfma_f32_32x32x16_bf16(pa3, PK(l3, h3), od, 0, 0, 0);
;     ...
; }
; DEV void pv_d0(f32x16* o, int vb, bf16x8 pa0, bf16x8 pa1, bf16x8 pa2, bf16x8 pa3) {
;   pv_one<0>(o[0], vb, pa0, pa1, pa2, pa3); pv_one<1>(o[1], vb, pa0, pa1, pa2, pa3); pv_one<2>(o[2], vb, pa0, pa1, pa2, pa3); pv_one<3>(o[3], vb, pa0, pa1, pa2, pa3);
	v_mfma_f32_32x32x16_bf16 v[64:79], v[206:209], v[210:213], v[64:79]
	v_mfma_f32_32x32x16_bf16 v[80:95], v[202:205], v[210:213], v[80:95]
	ds_read_b128 v[202:205], v171
	ds_read_b128 v[206:209], v172
	ds_read_b128 v[210:213], v177 offset:5120
	s_waitcnt lgkmcnt(0)
	v_mfma_f32_32x32x16_bf16 v[64:79], v[206:209], v[210:213], v[64:79]
	v_mfma_f32_32x32x16_bf16 v[80:95], v[202:205], v[210:213], v[80:95]
	ds_read_b128 v[202:205], v173
	ds_read_b128 v[206:209], v174
	ds_read_b128 v[210:213], v177 offset:6144
	s_waitcnt lgkmcnt(0)
	v_mfma_f32_32x32x16_bf16 v[64:79], v[206:209], v[210:213], v[64:79]
	v_mfma_f32_32x32x16_bf16 v[80:95], v[202:205], v[210:213], v[80:95]
	ds_read_b128 v[202:205], v176
	ds_read_b128 v[206:209], v178
	ds_read_b128 v[210:213], v177 offset:7168
	s_waitcnt lgkmcnt(0)
	v_mfma_f32_32x32x16_bf16 v[64:79], v[206:209], v[210:213], v[64:79]
	v_exp_f32_e32 v208, v132
	v_add_f32_e32 v132, 0, v125
	v_add_f32_e32 v132, v127, v132
	v_add_f32_e32 v132, v123, v132
	v_add_f32_e32 v132, v126, v132
	v_add_f32_e32 v132, v122, v132
	v_add_f32_e32 v132, v124, v132
	v_add_f32_e32 v132, v120, v132
	v_add_f32_e32 v132, v121, v132
	v_add_f32_e32 v132, v117, v132
	v_add_f32_e32 v132, v119, v132
	v_add_f32_e32 v132, v116, v132
	v_add_f32_e32 v132, v118, v132
	v_add_f32_e32 v132, v113, v132
	v_mfma_f32_32x32x16_bf16 v[80:95], v[202:205], v[210:213], v[80:95]
	v_exp_f32_e32 v204, v195
	v_add_f32_e32 v132, v115, v132
	v_exp_f32_e32 v205, v196
	v_add_f32_e32 v132, v112, v132
	v_exp_f32_e32 v206, v197
	v_add_f32_e32 v132, v114, v132
	v_exp_f32_e32 v207, v198
	v_add_f32_e32 v132, v201, v132
	v_add_f32_e32 v132, v204, v132
	v_add_f32_e32 v132, v205, v132
	v_add_f32_e32 v132, v206, v132
	v_exp_f32_e32 v209, v133
	v_add_f32_e32 v132, v207, v132
	v_exp_f32_e32 v210, v134
	v_add_f32_e32 v132, v130, v132
	v_exp_f32_e32 v211, v135
	v_add_f32_e32 v132, v131, v132
	v_add_f32_e32 v132, v208, v132
	v_add_f32_e32 v132, v209, v132
	v_exp_f32_e32 v212, v199
	v_add_f32_e32 v132, v210, v132
	v_exp_f32_e32 v213, v200
	v_add_f32_e32 v132, v211, v132
	v_add_f32_e32 v132, v193, v132
	v_add_f32_e32 v132, v129, v132
	v_add_f32_e32 v132, v212, v132
	v_add_f32_e32 v132, v213, v132
	v_add_f32_e32 v202, v128, v132
	v_mov_b32_e32 v203, v202
	v_cvt_pk_bf16_f32 v132, v125, v127
	v_cvt_pk_bf16_f32 v133, v123, v126
	v_cvt_pk_bf16_f32 v134, v122, v124
	v_cvt_pk_bf16_f32 v135, v120, v121
	s_nop 1
	v_permlane32_swap_b32_e32 v202, v203
	v_permlane32_swap_b32_e32 v132, v134
	v_permlane32_swap_b32_e32 v133, v135
	v_cvt_pk_bf16_f32 v194, v117, v119
	v_cvt_pk_bf16_f32 v195, v116, v118
	v_cvt_pk_bf16_f32 v196, v113, v115
	v_cvt_pk_bf16_f32 v197, v112, v114
	v_cvt_pk_bf16_f32 v198, v201, v204
	v_cvt_pk_bf16_f32 v199, v205, v206
	v_cvt_pk_bf16_f32 v200, v207, v130
	v_cvt_pk_bf16_f32 v201, v131, v208
	v_cvt_pk_bf16_f32 v204, v209, v210
	v_cvt_pk_bf16_f32 v205, v211, v193
	v_cvt_pk_bf16_f32 v206, v129, v212
	v_cvt_pk_bf16_f32 v207, v213, v128
	s_nop 0
	v_permlane32_swap_b32_e32 v194, v196
	v_permlane32_swap_b32_e32 v195, v197
	v_permlane32_swap_b32_e32 v198, v200
	v_permlane32_swap_b32_e32 v199, v201
	v_permlane32_swap_b32_e32 v204, v206
	v_permlane32_swap_b32_e32 v205, v207
	s_waitcnt vmcnt(2)
	ds_write_b128 v156, v[226:229] offset:49152
	ds_write_b128 v157, v[230:233] offset:49152
	ds_write_b128 v183, v[234:237]
	ds_read_b64_tr_b16 v[208:209], v152 offset:0
	ds_read_b64_tr_b16 v[210:211], v152 offset:0x800
	ds_read_b64_tr_b16 v[212:213], v152 offset:0x1000
	ds_read_b64_tr_b16 v[214:215], v152 offset:0x1800
	ds_read_b64_tr_b16 v[216:217], v152 offset:0x2000
	ds_read_b64_tr_b16 v[218:219], v152 offset:0x2800
	ds_read_b64_tr_b16 v[220:221], v152 offset:0x3000
	ds_read_b64_tr_b16 v[222:223], v152 offset:0x3800
	s_waitcnt lgkmcnt(6)
	s_nop 0
	v_mfma_f32_32x32x16_bf16 v[0:15], v[132:135], v[208:211], v[0:15]
	ds_read_b64_tr_b16 v[208:209], v152 offset:0x200
	ds_read_b64_tr_b16 v[210:211], v152 offset:0xa00
	s_waitcnt lgkmcnt(6)
	v_mfma_f32_32x32x16_bf16 v[0:15], v[194:197], v[212:215], v[0:15]
	ds_read_b64_tr_b16 v[212:213], v152 offset:0x1200
	ds_read_b64_tr_b16 v[214:215], v152 offset:0x1a00
	s_waitcnt lgkmcnt(6)
	v_mfma_f32_32x32x16_bf16 v[0:15], v[198:201], v[216:219], v[0:15]
	ds_read_b64_tr_b16 v[216:217], v152 offset:0x2200
	ds_read_b64_tr_b16 v[218:219], v152 offset:0x2a00
	s_waitcnt lgkmcnt(6)
	v_mfma_f32_32x32x16_bf16 v[0:15], v[204:207], v[220:223], v[0:15]
	ds_read_b64_tr_b16 v[220:221], v152 offset:0x3200
	ds_read_b64_tr_b16 v[222:223], v152 offset:0x3a00
	s_waitcnt lgkmcnt(6)
	v_mfma_f32_32x32x16_bf16 v[48:63], v[132:135], v[208:211], v[48:63]
	ds_read_b64_tr_b16 v[208:209], v152 offset:0x400
	ds_read_b64_tr_b16 v[210:211], v152 offset:0xc00
	s_waitcnt lgkmcnt(6)
; #define SBAR() __builtin_amdgcn_sched_barrier(0)
; DEV void partialSM(f32x16& p0, f32x16& p1, float& m_reg, float& mn, float& alpha) {
;   constexpr float C = SCALE * 1.4426950408889634f;
;   float pmax = p0[0];
; #pragma unroll
;   for (int r = 1; r < 16; ++r) pmax = fmaxf(pmax, p0[r]);
; #pragma unroll
;   for (int r = 0; r < 16; ++r) pmax = fmaxf(pmax, p1[r]);
;   { auto rr = __builtin_amdgcn_permlane32_swap(__float_as_uint(pmax), __float_as_uint(pmax), false, false);
;     pmax = fmaxf(__uint_as_float(rr[0]), __uint_as_float(rr[1])); }
;   if (__builtin_expect(__all(pmax - m_reg <= THR / SCALE), 1)) { mn = m_reg; alpha = 1.f; }
;   else { mn = fmaxf(m_reg, pmax); alpha = __builtin_amdgcn_exp2f((m_reg - mn) * C); m_reg = mn; }
; template <int D0> DEV void pv_one(f32x16& od, int vb, bf16x8 pa0, bf16x8 pa1, bf16x8 pa2, bf16x8 pa3) {
;   const s16x4 l0 = tr_read<v_rd_off(D0, 0, 0)>(vb), h0 = tr_read<v_rd_off(D0, 0, 1)>(vb), l1 = tr_read<v_rd_off(D0, 1, 0)>(vb), h1 = tr_read<v_rd_off(D0, 1, 1)>(vb);
;   const s16x4 l2 = tr_read<v_rd_off(D0, 2, 0)>(vb), h2 = tr_read<v_rd_off(D0, 2, 1)>(vb), l3 = tr_read<v_rd_off(D0, 3, 0)>(vb), h3 = tr_read<v_rd_off(D0, 3, 1)>(vb);
;   asm volatile("s_waitcnt lgkmcnt(0)" ::: "memory"); SBAR();
;     ...
;   od = __builtin_amdgcn_mfma_f32_32x32x16_bf16(pa0, PK(l0, h0), od, 0, 0, 0);
;   od = __builtin_amdgcn_mfma_f32_32x32x16_bf16(pa1, PK(l1, h1), od, 0, 0, 0);
;   od = __builtin_amdgcn_mfma_f32_32x32x16_bf16(pa2, PK(l2, h2), od, 0, 0, 0);
;   od = __builtin_amdgcn_mfma_f32_32x32x16_bf16(pa3, PK(l3, h3), od, 0, 0, 0);
;     ...
; }
; DEV void pv_d0(f32x16* o, int vb, bf16x8 pa0, bf16x8 pa1, bf16x8 pa2, bf16x8 pa3) {
;   pv_one<0>(o[0], vb, pa0, pa1, pa2, pa3); pv_one<1>(o[1], vb, pa0, pa1, pa2, pa3); pv_one<2>(o[2], vb, pa0, pa1, pa2, pa3); pv_one<3>(o[3], vb, pa0, pa1, pa2, pa3);
	v_mfma_f32_32x32x16_bf16 v[48:63], v[194:197], v[212:215], v[48:63]
	ds_read_b64_tr_b16 v[212:213], v152 offset:0x1400
	ds_read_b64_tr_b16 v[214:215], v152 offset:0x1c00
	s_waitcnt lgkmcnt(6)
	v_mfma_f32_32x32x16_bf16 v[48:63], v[198:201], v[216:219], v[48:63]
	ds_read_b64_tr_b16 v[216:217], v152 offset:0x2400
	ds_read_b64_tr_b16 v[218:219], v152 offset:0x2c00
	s_waitcnt lgkmcnt(6)
	v_mfma_f32_32x32x16_bf16 v[48:63], v[204:207], v[220:223], v[48:63]
	ds_read_b64_tr_b16 v[220:221], v152 offset:0x3400
	ds_read_b64_tr_b16 v[222:223], v152 offset:0x3c00
	s_waitcnt lgkmcnt(6)
	v_mfma_f32_32x32x16_bf16 v[32:47], v[132:135], v[208:211], v[32:47]
	ds_read_b64_tr_b16 v[208:209], v152 offset:0x600
	ds_read_b64_tr_b16 v[210:211], v152 offset:0xe00
	s_waitcnt lgkmcnt(6)
	v_mfma_f32_32x32x16_bf16 v[32:47], v[194:197], v[212:215], v[32:47]
	ds_read_b64_tr_b16 v[212:213], v152 offset:0x1600
	ds_read_b64_tr_b16 v[214:215], v152 offset:0x1e00
	s_waitcnt lgkmcnt(6)
	v_mfma_f32_32x32x16_bf16 v[32:47], v[198:201], v[216:219], v[32:47]
	ds_read_b64_tr_b16 v[216:217], v152 offset:0x2600
	ds_read_b64_tr_b16 v[218:219], v152 offset:0x2e00
	s_waitcnt lgkmcnt(6)
	v_mfma_f32_32x32x16_bf16 v[32:47], v[204:207], v[220:223], v[32:47]
	ds_read_b64_tr_b16 v[220:221], v152 offset:0x3600
	ds_read_b64_tr_b16 v[222:223], v152 offset:0x3e00
	s_waitcnt lgkmcnt(6)
	v_mfma_f32_32x32x16_bf16 v[16:31], v[132:135], v[208:211], v[16:31]
	v_max_f32_e32 v132, v81, v81
	v_max_f32_e32 v133, v80, v80
	v_max_f32_e32 v132, v133, v132
	v_max3_f32 v132, v132, v82, v83
	v_max3_f32 v132, v132, v84, v85
	v_max3_f32 v132, v132, v86, v87
	v_max3_f32 v132, v132, v88, v89
	v_max3_f32 v132, v132, v90, v91
	v_max3_f32 v132, v132, v92, v93
	s_waitcnt lgkmcnt(4)
	v_mfma_f32_32x32x16_bf16 v[16:31], v[194:197], v[212:215], v[16:31]
	v_max3_f32 v132, v132, v94, v95
	v_max3_f32 v132, v132, v64, v65
	v_max3_f32 v132, v132, v66, v67
	v_max3_f32 v132, v132, v68, v69
	v_max3_f32 v132, v132, v70, v71
	v_max3_f32 v132, v132, v72, v73
	v_max3_f32 v132, v132, v74, v75
	v_max3_f32 v132, v132, v76, v77
	s_waitcnt lgkmcnt(2)
	v_mfma_f32_32x32x16_bf16 v[16:31], v[198:201], v[216:219], v[16:31]
	v_max3_f32 v132, v132, v78, v79
	v_mov_b32_e32 v133, v132
	s_nop 1
	v_permlane32_swap_b32_e32 v132, v133
	v_max_f32_e32 v133, v133, v133
	v_max_f32_e32 v132, v132, v132
	v_max_f32_e32 v132, v132, v133
	v_sub_f32_e32 v133, v132, v192
	v_cmp_ge_f32_e32 vcc, s72, v133
	v_max_f32_e32 v133, v192, v192
	v_max_f32_e32 v132, v133, v132
	s_waitcnt lgkmcnt(0)
	v_mfma_f32_32x32x16_bf16 v[16:31], v[204:207], v[220:223], v[16:31]
	v_sub_f32_e32 v133, v192, v132
	v_mul_f32_e32 v133, 0x3dd53b94, v133
	v_exp_f32_e32 v133, v133
	s_cmp_eq_u64 vcc, exec
	s_cselect_b64 s[4:5], -1, 0
	v_cndmask_b32_e64 v133, v133, 1.0, s[4:5]
	v_cmp_gt_f32_e32 vcc, 1.0, v133
	s_cbranch_vccz .LBB0_312
	s_and_saveexec_b64 s[8:9], s[6:7]
	ds_write_b32 v150, v133 offset:128
	s_or_b64 exec, exec, s[8:9]
	s_waitcnt lgkmcnt(0)
	v_add_u32_e32 v124, v139, v136
	ds_read_b128 v[112:115], v124 offset:224
	ds_read_b128 v[116:119], v124 offset:192
	ds_read_b128 v[120:123], v124 offset:160
	ds_read_b128 v[124:127], v124 offset:128
	s_waitcnt lgkmcnt(3)
	v_pk_mul_f32 v[12:13], v[12:13], v[112:113]
	s_waitcnt lgkmcnt(2)
	v_pk_mul_f32 v[8:9], v[8:9], v[116:117]
	s_waitcnt lgkmcnt(1)
	v_pk_mul_f32 v[4:5], v[4:5], v[120:121]
	v_pk_mul_f32 v[14:15], v[14:15], v[114:115]
	v_pk_mul_f32 v[10:11], v[10:11], v[118:119]
	v_pk_mul_f32 v[6:7], v[6:7], v[122:123]
	s_waitcnt lgkmcnt(0)
	v_pk_mul_f32 v[2:3], v[2:3], v[126:127]
	v_pk_mul_f32 v[0:1], v[0:1], v[124:125]
	v_pk_mul_f32 v[60:61], v[60:61], v[112:113]
	v_pk_mul_f32 v[56:57], v[56:57], v[116:117]
	v_pk_mul_f32 v[52:53], v[52:53], v[120:121]
	v_pk_mul_f32 v[62:63], v[62:63], v[114:115]
	v_pk_mul_f32 v[58:59], v[58:59], v[118:119]
	v_pk_mul_f32 v[54:55], v[54:55], v[122:123]
	v_pk_mul_f32 v[50:51], v[50:51], v[126:127]
	v_pk_mul_f32 v[48:49], v[48:49], v[124:125]
	v_pk_mul_f32 v[44:45], v[44:45], v[112:113]
	v_pk_mul_f32 v[40:41], v[40:41], v[116:117]
	v_pk_mul_f32 v[36:37], v[36:37], v[120:121]
	v_pk_mul_f32 v[46:47], v[46:47], v[114:115]
	v_pk_mul_f32 v[42:43], v[42:43], v[118:119]
	v_pk_mul_f32 v[38:39], v[38:39], v[122:123]
	v_pk_mul_f32 v[34:35], v[34:35], v[126:127]
	v_pk_mul_f32 v[32:33], v[32:33], v[124:125]
	v_pk_mul_f32 v[28:29], v[28:29], v[112:113]
	v_pk_mul_f32 v[24:25], v[24:25], v[116:117]
	v_pk_mul_f32 v[20:21], v[20:21], v[120:121]
	v_pk_mul_f32 v[30:31], v[30:31], v[114:115]
	v_pk_mul_f32 v[26:27], v[26:27], v[118:119]
	v_pk_mul_f32 v[22:23], v[22:23], v[122:123]
	v_pk_mul_f32 v[18:19], v[18:19], v[126:127]
	v_pk_mul_f32 v[16:17], v[16:17], v[124:125]
